# up/down GEMM K-loops: last 4 LDS-DMA address adds per iteration removed (SGPR base stepped in place)
# baseline (speedup 1.0000x reference)
; #define PG8_STAGE(bufoff, gbase, voff) do { _Pragma("unroll") for (int _i = 0; _i < 2; ++_i) \
;         __builtin_amdgcn_global_load_lds((const unsigned*)((const char*)(gbase) + (voff)[_i]), (LAS unsigned*)(lds + (bufoff) + ldsw + _i * 8192), 16, 0, 0); } while (0)
; #define PG8_LDA(dst, b, h) do { _Pragma("unroll") for (int m = 0; m < 4; ++m) _Pragma("unroll") for (int k = 0; k < 2; ++k) dst[m][k] = *(const LAS bf16x8*)(lds + PG8_SA(b, h) + aoff + m * 2048 + k * 1024); } while (0)
; #define PG8_LDB(dst, b, h) do { _Pragma("unroll") for (int n = 0; n < 2; ++n) _Pragma("unroll") for (int k = 0; k < 2; ++k) dst[n][k] = *(const LAS bf16x8*)(lds + PG8_SB(b, h) + boff + n * 2048 + k * 1024); } while (0)
; #define PG8_MMA(ai, bj, At, Bt) do { __builtin_amdgcn_s_setprio(1); _Pragma("unroll") for (int m = 0; m < 4; ++m) _Pragma("unroll") for (int n = 0; n < 2; ++n) _Pragma("unroll") for (int k = 0; k < 2; ++k) \
;         acc[ai][bj][m][n] = __builtin_amdgcn_mfma_f32_16x16x32_bf16(Bt[n][k], At[m][k], acc[ai][bj][m][n], 0, 0, 0); __builtin_amdgcn_s_setprio(0); } while (0)
; #define PG8_WAIT_V(n) asm volatile("s_waitcnt vmcnt(" #n ")" ::: "memory")
; #define PG8_WAIT_L(n) asm volatile("s_waitcnt lgkmcnt(" #n ")" ::: "memory")
; #define PG8_BAR __builtin_amdgcn_s_barrier()
; #define PG8_SCHED __builtin_amdgcn_sched_barrier(0)
; template <class Epi, class Sched>
; DI void gemm_phase(LAS unsigned char* lds, const int K, const Sched& S, const Epi& E) {
;     ...
;             const bool last = (t == nt - 2);
;             const char* a1 = cA + (size_t)(t + 1) * kstep;
;             const char* a2 = last ? nA : cA + (size_t)(t + 2) * kstep; const char* b2 = last ? nB : cB + (size_t)(t + 2) * kstep;
;             const char* a3 = a2 + kstep; const char* b3 = b2 + kstep;
;             PG8_LDB(B0, 0, 0); PG8_LDB(B1, 0, 1); PG8_SCHED; PG8_LDA(At, 0, 0); PG8_STAGE(PG8_SA(1, 1), a1 + hstep, voffA);
;             PG8_WAIT_V(8); PG8_WAIT_L(0); PG8_BAR; PG8_MMA(0, 0, At, B0); PG8_MMA(0, 1, At, B1); PG8_BAR; PG8_SCHED;
;             PG8_LDA(At, 0, 1); PG8_STAGE(PG8_SB(0, 0), b2, voffB); PG8_STAGE(PG8_SB(0, 1), b2 + hstep, voffB); PG8_STAGE(PG8_SA(0, 0), a2, voffA);
;             PG8_WAIT_V(8); PG8_WAIT_L(0); PG8_BAR; PG8_MMA(1, 0, At, B0); PG8_MMA(1, 1, At, B1); PG8_BAR; PG8_SCHED;
.LBB0_1086:
	s_add_u32 s48, s68, 0xfffc0080
	s_addc_u32 s49, s69, -1
	s_add_i32 vcc_hi, 0, 0x10000
	s_cmp_eq_u32 vcc_lo, 12
	s_cselect_b32 s73, s65, s49
	s_cselect_b32 s72, s64, s48
	v_add_u32_e32 v145, vcc_hi, v143
	s_cselect_b32 s71, s67, s63
	s_cselect_b32 s70, s66, s61
	s_add_i32 s94, 0, 0x14000
	ds_read_b128 v[146:149], v145
	ds_read_b128 v[150:153], v145 offset:1024
	ds_read_b128 v[154:157], v145 offset:2048
	ds_read_b128 v[158:161], v145 offset:3072
	v_add_u32_e32 v145, s94, v143
	ds_read_b128 v[162:165], v145
	ds_read_b128 v[166:169], v145 offset:1024
	ds_read_b128 v[170:173], v145 offset:2048
	ds_read_b128 v[174:177], v145 offset:3072
	s_nop 0
	s_add_i32 m0, s59, 0xc000
	ds_read_b128 v[182:185], v144
	ds_read_b128 v[190:193], v144 offset:1024
	ds_read_b128 v[194:197], v144 offset:2048
	ds_read_b128 v[198:201], v144 offset:3072
	ds_read_b128 v[202:205], v144 offset:4096
	ds_read_b128 v[212:215], v144 offset:5120
	ds_read_b128 v[216:219], v144 offset:6144
	ds_read_b128 v[220:223], v144 offset:7168
	global_load_lds_dwordx4 v140, s[68:69]
	s_nop 0
	s_add_i32 m0, s59, 0xe000
	s_nop 0
	global_load_lds_dwordx4 v138, s[68:69]
	s_waitcnt vmcnt(8)
	s_waitcnt lgkmcnt(0)
	s_barrier
	s_nop 0
	s_waitcnt lgkmcnt(0)
	v_mfma_f32_16x16x32_bf16 v[126:129], v[146:149], v[182:185], v[126:129]
	v_mfma_f32_16x16x32_bf16 v[122:125], v[154:157], v[182:185], v[122:125]
	v_mfma_f32_16x16x32_bf16 v[118:121], v[146:149], v[194:197], v[118:121]
	v_mfma_f32_16x16x32_bf16 v[114:117], v[154:157], v[194:197], v[114:117]
	v_mfma_f32_16x16x32_bf16 v[102:105], v[146:149], v[202:205], v[102:105]
	v_mfma_f32_16x16x32_bf16 v[98:101], v[154:157], v[202:205], v[98:101]
	v_mfma_f32_16x16x32_bf16 v[86:89], v[146:149], v[216:219], v[86:89]
	v_mfma_f32_16x16x32_bf16 v[82:85], v[154:157], v[216:219], v[82:85]
	v_mfma_f32_16x16x32_bf16 v[126:129], v[150:153], v[190:193], v[126:129]
	v_mfma_f32_16x16x32_bf16 v[122:125], v[158:161], v[190:193], v[122:125]
	v_mfma_f32_16x16x32_bf16 v[118:121], v[150:153], v[198:201], v[118:121]
	v_mfma_f32_16x16x32_bf16 v[114:117], v[158:161], v[198:201], v[114:117]
	v_mfma_f32_16x16x32_bf16 v[102:105], v[150:153], v[212:215], v[102:105]
	v_mfma_f32_16x16x32_bf16 v[98:101], v[158:161], v[212:215], v[98:101]
	v_mfma_f32_16x16x32_bf16 v[86:89], v[150:153], v[220:223], v[86:89]
	v_mfma_f32_16x16x32_bf16 v[82:85], v[158:161], v[220:223], v[82:85]
	s_nop 0
	s_nop 0
	v_mfma_f32_16x16x32_bf16 v[110:113], v[162:165], v[182:185], v[110:113]
	v_mfma_f32_16x16x32_bf16 v[106:109], v[170:173], v[182:185], v[106:109]
	v_mfma_f32_16x16x32_bf16 v[94:97], v[162:165], v[194:197], v[94:97]
	v_mfma_f32_16x16x32_bf16 v[90:93], v[170:173], v[194:197], v[90:93]
	v_mfma_f32_16x16x32_bf16 v[78:81], v[162:165], v[202:205], v[78:81]
	v_mfma_f32_16x16x32_bf16 v[74:77], v[170:173], v[202:205], v[74:77]
	v_mfma_f32_16x16x32_bf16 v[70:73], v[162:165], v[216:219], v[70:73]
	v_mfma_f32_16x16x32_bf16 v[66:69], v[170:173], v[216:219], v[66:69]
	v_mfma_f32_16x16x32_bf16 v[110:113], v[166:169], v[190:193], v[110:113]
	v_mfma_f32_16x16x32_bf16 v[106:109], v[174:177], v[190:193], v[106:109]
	v_mfma_f32_16x16x32_bf16 v[94:97], v[166:169], v[198:201], v[94:97]
	v_mfma_f32_16x16x32_bf16 v[90:93], v[174:177], v[198:201], v[90:93]
	v_mfma_f32_16x16x32_bf16 v[78:81], v[166:169], v[212:215], v[78:81]
	v_mfma_f32_16x16x32_bf16 v[74:77], v[174:177], v[212:215], v[74:77]
	v_mfma_f32_16x16x32_bf16 v[70:73], v[166:169], v[220:223], v[70:73]
	v_mfma_f32_16x16x32_bf16 v[66:69], v[174:177], v[220:223], v[66:69]
	s_nop 0
	s_barrier
	s_add_i32 s48, vcc_hi, s78
	s_nop 0
	s_mov_b32 m0, s48
	ds_read_b128 v[182:185], v144 offset:16384
	ds_read_b128 v[190:193], v144 offset:17408
	ds_read_b128 v[194:197], v144 offset:18432
	ds_read_b128 v[198:201], v144 offset:19456
	ds_read_b128 v[202:205], v144 offset:20480
	ds_read_b128 v[212:215], v144 offset:21504
	ds_read_b128 v[216:219], v144 offset:22528
	ds_read_b128 v[220:223], v144 offset:23552
	global_load_lds_dwordx4 v134, s[70:71]
	s_add_i32 m0, s48, 0x2000
	s_add_u32 s48, s70, 0x40000
	s_nop 0
	s_addc_u32 s49, s71, 0
	s_add_i32 s94, s94, s78
	global_load_lds_dwordx4 v130, s[70:71]
	s_nop 0
	s_mov_b32 m0, s94
	s_nop 0
	global_load_lds_dwordx4 v134, s[48:49]
	s_nop 0
	s_add_i32 m0, s94, 0x2000
	s_nop 0
	global_load_lds_dwordx4 v130, s[48:49]
	s_nop 0
	s_add_u32 s98, s72, s90
	s_addc_u32 s99, s73, s91
	s_mov_b32 m0, s59
	s_nop 0
	global_load_lds_dwordx4 v136, s[72:73]
	s_mov_b32 m0, s80
	s_nop 0
	global_load_lds_dwordx4 v132, s[72:73]
	s_waitcnt vmcnt(8)
	s_waitcnt lgkmcnt(0)
	s_barrier
; #define PG8_STAGE(bufoff, gbase, voff) do { _Pragma("unroll") for (int _i = 0; _i < 2; ++_i) \
;         __builtin_amdgcn_global_load_lds((const unsigned*)((const char*)(gbase) + (voff)[_i]), (LAS unsigned*)(lds + (bufoff) + ldsw + _i * 8192), 16, 0, 0); } while (0)
; #define PG8_LDA(dst, b, h) do { _Pragma("unroll") for (int m = 0; m < 4; ++m) _Pragma("unroll") for (int k = 0; k < 2; ++k) dst[m][k] = *(const LAS bf16x8*)(lds + PG8_SA(b, h) + aoff + m * 2048 + k * 1024); } while (0)
; #define PG8_LDB(dst, b, h) do { _Pragma("unroll") for (int n = 0; n < 2; ++n) _Pragma("unroll") for (int k = 0; k < 2; ++k) dst[n][k] = *(const LAS bf16x8*)(lds + PG8_SB(b, h) + boff + n * 2048 + k * 1024); } while (0)
; #define PG8_MMA(ai, bj, At, Bt) do { __builtin_amdgcn_s_setprio(1); _Pragma("unroll") for (int m = 0; m < 4; ++m) _Pragma("unroll") for (int n = 0; n < 2; ++n) _Pragma("unroll") for (int k = 0; k < 2; ++k) \
;         acc[ai][bj][m][n] = __builtin_amdgcn_mfma_f32_16x16x32_bf16(Bt[n][k], At[m][k], acc[ai][bj][m][n], 0, 0, 0); __builtin_amdgcn_s_setprio(0); } while (0)
; #define PG8_WAIT_V(n) asm volatile("s_waitcnt vmcnt(" #n ")" ::: "memory")
; #define PG8_WAIT_L(n) asm volatile("s_waitcnt lgkmcnt(" #n ")" ::: "memory")
; #define PG8_BAR __builtin_amdgcn_s_barrier()
; #define PG8_SCHED __builtin_amdgcn_sched_barrier(0)
; template <class Epi, class Sched>
; DI void gemm_phase(LAS unsigned char* lds, const int K, const Sched& S, const Epi& E) {
;     ...
;             PG8_WAIT_V(8); PG8_WAIT_L(0); PG8_BAR; PG8_MMA(1, 0, At, B0); PG8_MMA(1, 1, At, B1); PG8_BAR; PG8_SCHED;
;             PG8_LDB(B0, 1, 0); PG8_LDB(B1, 1, 1); PG8_SCHED; PG8_LDA(At, 1, 0); PG8_STAGE(PG8_SA(0, 1), a2 + hstep, voffA);
;             PG8_WAIT_V(8); PG8_WAIT_L(0); PG8_BAR; PG8_MMA(0, 0, At, B0); PG8_MMA(0, 1, At, B1); PG8_BAR; PG8_SCHED;
	s_nop 0
	s_waitcnt lgkmcnt(0)
	v_mfma_f32_16x16x32_bf16 v[62:65], v[146:149], v[182:185], v[62:65]
	v_mfma_f32_16x16x32_bf16 v[58:61], v[154:157], v[182:185], v[58:61]
	v_mfma_f32_16x16x32_bf16 v[54:57], v[146:149], v[194:197], v[54:57]
	v_mfma_f32_16x16x32_bf16 v[50:53], v[154:157], v[194:197], v[50:53]
	v_mfma_f32_16x16x32_bf16 v[38:41], v[146:149], v[202:205], v[38:41]
	v_mfma_f32_16x16x32_bf16 v[34:37], v[154:157], v[202:205], v[34:37]
	v_mfma_f32_16x16x32_bf16 v[22:25], v[146:149], v[216:219], v[22:25]
	v_mfma_f32_16x16x32_bf16 v[18:21], v[154:157], v[216:219], v[18:21]
	v_mfma_f32_16x16x32_bf16 v[62:65], v[150:153], v[190:193], v[62:65]
	v_mfma_f32_16x16x32_bf16 v[58:61], v[158:161], v[190:193], v[58:61]
	v_mfma_f32_16x16x32_bf16 v[54:57], v[150:153], v[198:201], v[54:57]
	v_mfma_f32_16x16x32_bf16 v[50:53], v[158:161], v[198:201], v[50:53]
	v_mfma_f32_16x16x32_bf16 v[38:41], v[150:153], v[212:215], v[38:41]
	v_mfma_f32_16x16x32_bf16 v[34:37], v[158:161], v[212:215], v[34:37]
	v_mfma_f32_16x16x32_bf16 v[22:25], v[150:153], v[220:223], v[22:25]
	v_mfma_f32_16x16x32_bf16 v[18:21], v[158:161], v[220:223], v[18:21]
	s_nop 0
	s_nop 0
	v_mfma_f32_16x16x32_bf16 v[46:49], v[162:165], v[182:185], v[46:49]
	v_mfma_f32_16x16x32_bf16 v[42:45], v[170:173], v[182:185], v[42:45]
	v_mfma_f32_16x16x32_bf16 v[30:33], v[162:165], v[194:197], v[30:33]
	v_mfma_f32_16x16x32_bf16 v[26:29], v[170:173], v[194:197], v[26:29]
	v_mfma_f32_16x16x32_bf16 v[14:17], v[162:165], v[202:205], v[14:17]
	v_mfma_f32_16x16x32_bf16 v[10:13], v[170:173], v[202:205], v[10:13]
	v_mfma_f32_16x16x32_bf16 v[6:9], v[162:165], v[216:219], v[6:9]
	v_mfma_f32_16x16x32_bf16 v[2:5], v[170:173], v[216:219], v[2:5]
	v_mfma_f32_16x16x32_bf16 v[46:49], v[166:169], v[190:193], v[46:49]
	v_mfma_f32_16x16x32_bf16 v[42:45], v[174:177], v[190:193], v[42:45]
	v_mfma_f32_16x16x32_bf16 v[30:33], v[166:169], v[198:201], v[30:33]
	v_mfma_f32_16x16x32_bf16 v[26:29], v[174:177], v[198:201], v[26:29]
	v_mfma_f32_16x16x32_bf16 v[14:17], v[166:169], v[212:215], v[14:17]
	v_mfma_f32_16x16x32_bf16 v[10:13], v[174:177], v[212:215], v[10:13]
	v_mfma_f32_16x16x32_bf16 v[6:9], v[166:169], v[220:223], v[6:9]
	v_mfma_f32_16x16x32_bf16 v[2:5], v[174:177], v[220:223], v[2:5]
	s_nop 0
	s_barrier
	s_add_i32 s94, 0, 0x18000
	v_add_u32_e32 v145, s94, v143
	s_add_i32 vcc_hi, 0, 0x1c000
	ds_read_b128 v[146:149], v145
	ds_read_b128 v[150:153], v145 offset:1024
	ds_read_b128 v[154:157], v145 offset:2048
	ds_read_b128 v[158:161], v145 offset:3072
	v_add_u32_e32 v145, vcc_hi, v143
	ds_read_b128 v[162:165], v145
	ds_read_b128 v[166:169], v145 offset:1024
	ds_read_b128 v[170:173], v145 offset:2048
	ds_read_b128 v[174:177], v145 offset:3072
	s_add_u32 s48, s72, 0x40000
	s_addc_u32 s49, s73, 0
	s_mov_b32 m0, s81
	s_nop 0
	ds_read_b128 v[182:185], v144 offset:32768
	ds_read_b128 v[190:193], v144 offset:33792
	ds_read_b128 v[194:197], v144 offset:34816
	ds_read_b128 v[198:201], v144 offset:35840
	ds_read_b128 v[202:205], v144 offset:36864
	ds_read_b128 v[212:215], v144 offset:37888
	ds_read_b128 v[216:219], v144 offset:38912
	ds_read_b128 v[220:223], v144 offset:39936
	global_load_lds_dwordx4 v136, s[48:49]
	s_nop 0
	s_mov_b32 m0, s83
	s_nop 0
	global_load_lds_dwordx4 v132, s[48:49]
	s_waitcnt vmcnt(8)
	s_waitcnt lgkmcnt(0)
	s_barrier
	s_nop 0
	s_waitcnt lgkmcnt(0)
	v_mfma_f32_16x16x32_bf16 v[126:129], v[146:149], v[182:185], v[126:129]
	v_mfma_f32_16x16x32_bf16 v[122:125], v[154:157], v[182:185], v[122:125]
	v_mfma_f32_16x16x32_bf16 v[118:121], v[146:149], v[194:197], v[118:121]
	v_mfma_f32_16x16x32_bf16 v[114:117], v[154:157], v[194:197], v[114:117]
	v_mfma_f32_16x16x32_bf16 v[102:105], v[146:149], v[202:205], v[102:105]
	v_mfma_f32_16x16x32_bf16 v[98:101], v[154:157], v[202:205], v[98:101]
	v_mfma_f32_16x16x32_bf16 v[86:89], v[146:149], v[216:219], v[86:89]
	v_mfma_f32_16x16x32_bf16 v[82:85], v[154:157], v[216:219], v[82:85]
	v_mfma_f32_16x16x32_bf16 v[126:129], v[150:153], v[190:193], v[126:129]
	v_mfma_f32_16x16x32_bf16 v[122:125], v[158:161], v[190:193], v[122:125]
	v_mfma_f32_16x16x32_bf16 v[118:121], v[150:153], v[198:201], v[118:121]
	v_mfma_f32_16x16x32_bf16 v[114:117], v[158:161], v[198:201], v[114:117]
	v_mfma_f32_16x16x32_bf16 v[102:105], v[150:153], v[212:215], v[102:105]
	v_mfma_f32_16x16x32_bf16 v[98:101], v[158:161], v[212:215], v[98:101]
	v_mfma_f32_16x16x32_bf16 v[86:89], v[150:153], v[220:223], v[86:89]
	v_mfma_f32_16x16x32_bf16 v[82:85], v[158:161], v[220:223], v[82:85]
	s_nop 0
	s_nop 0
	v_mfma_f32_16x16x32_bf16 v[110:113], v[162:165], v[182:185], v[110:113]
	v_mfma_f32_16x16x32_bf16 v[106:109], v[170:173], v[182:185], v[106:109]
	v_mfma_f32_16x16x32_bf16 v[94:97], v[162:165], v[194:197], v[94:97]
	v_mfma_f32_16x16x32_bf16 v[90:93], v[170:173], v[194:197], v[90:93]
	v_mfma_f32_16x16x32_bf16 v[78:81], v[162:165], v[202:205], v[78:81]
	v_mfma_f32_16x16x32_bf16 v[74:77], v[170:173], v[202:205], v[74:77]
	v_mfma_f32_16x16x32_bf16 v[70:73], v[162:165], v[216:219], v[70:73]
	v_mfma_f32_16x16x32_bf16 v[66:69], v[170:173], v[216:219], v[66:69]
	v_mfma_f32_16x16x32_bf16 v[110:113], v[166:169], v[190:193], v[110:113]
	v_mfma_f32_16x16x32_bf16 v[106:109], v[174:177], v[190:193], v[106:109]
	v_mfma_f32_16x16x32_bf16 v[94:97], v[166:169], v[198:201], v[94:97]
	v_mfma_f32_16x16x32_bf16 v[90:93], v[174:177], v[198:201], v[90:93]
	v_mfma_f32_16x16x32_bf16 v[78:81], v[166:169], v[212:215], v[78:81]
	v_mfma_f32_16x16x32_bf16 v[74:77], v[174:177], v[212:215], v[74:77]
	v_mfma_f32_16x16x32_bf16 v[70:73], v[166:169], v[220:223], v[70:73]
	v_mfma_f32_16x16x32_bf16 v[66:69], v[174:177], v[220:223], v[66:69]
	s_nop 0
	s_barrier
; #define PG8_STAGE(bufoff, gbase, voff) do { _Pragma("unroll") for (int _i = 0; _i < 2; ++_i) \
;         __builtin_amdgcn_global_load_lds((const unsigned*)((const char*)(gbase) + (voff)[_i]), (LAS unsigned*)(lds + (bufoff) + ldsw + _i * 8192), 16, 0, 0); } while (0)
; #define PG8_LDA(dst, b, h) do { _Pragma("unroll") for (int m = 0; m < 4; ++m) _Pragma("unroll") for (int k = 0; k < 2; ++k) dst[m][k] = *(const LAS bf16x8*)(lds + PG8_SA(b, h) + aoff + m * 2048 + k * 1024); } while (0)
; #define PG8_MMA(ai, bj, At, Bt) do { __builtin_amdgcn_s_setprio(1); _Pragma("unroll") for (int m = 0; m < 4; ++m) _Pragma("unroll") for (int n = 0; n < 2; ++n) _Pragma("unroll") for (int k = 0; k < 2; ++k) \
;         acc[ai][bj][m][n] = __builtin_amdgcn_mfma_f32_16x16x32_bf16(Bt[n][k], At[m][k], acc[ai][bj][m][n], 0, 0, 0); __builtin_amdgcn_s_setprio(0); } while (0)
; #define PG8_WAIT_V(n) asm volatile("s_waitcnt vmcnt(" #n ")" ::: "memory")
; #define PG8_WAIT_L(n) asm volatile("s_waitcnt lgkmcnt(" #n ")" ::: "memory")
; #define PG8_BAR __builtin_amdgcn_s_barrier()
; #define PG8_SCHED __builtin_amdgcn_sched_barrier(0)
; template <class Epi, class Sched>
; DI void gemm_phase(LAS unsigned char* lds, const int K, const Sched& S, const Epi& E) {
;     ...
;             PG8_LDA(At, 1, 1); PG8_STAGE(PG8_SB(1, 0), b3, voffB); PG8_STAGE(PG8_SB(1, 1), b3 + hstep, voffB); PG8_STAGE(PG8_SA(1, 0), a3, voffA);
;             PG8_WAIT_V(8); PG8_WAIT_L(0); PG8_BAR; PG8_MMA(1, 0, At, B0); PG8_MMA(1, 1, At, B1); PG8_BAR; PG8_SCHED;
;         }
;         if (wr == 0) PG8_BAR;
	s_add_i32 s48, s94, s78
	s_add_u32 s70, s70, 0x80
	s_addc_u32 s71, s71, 0
	s_mov_b32 m0, s48
	ds_read_b128 v[182:185], v144 offset:49152
	ds_read_b128 v[190:193], v144 offset:50176
	ds_read_b128 v[194:197], v144 offset:51200
	ds_read_b128 v[198:201], v144 offset:52224
	ds_read_b128 v[202:205], v144 offset:53248
	ds_read_b128 v[212:215], v144 offset:54272
	ds_read_b128 v[216:219], v144 offset:55296
	ds_read_b128 v[220:223], v144 offset:56320
	global_load_lds_dwordx4 v134, s[70:71]
	s_add_i32 m0, s48, 0x2000
	s_add_u32 s48, s70, 0x40000
	s_nop 0
	s_addc_u32 s49, s71, 0
	global_load_lds_dwordx4 v130, s[70:71]
	s_add_i32 s70, vcc_hi, s78
	s_nop 0
	s_mov_b32 m0, s70
	s_nop 0
	global_load_lds_dwordx4 v134, s[48:49]
	s_nop 0
	s_add_i32 m0, s70, 0x2000
	s_nop 0
	global_load_lds_dwordx4 v130, s[48:49]
	s_nop 0
	s_mov_b32 m0, s95
	s_nop 0
	global_load_lds_dwordx4 v136, s[98:99]
	s_nop 0
	s_mov_b32 m0, s42
	s_nop 0
	global_load_lds_dwordx4 v132, s[98:99]
	s_waitcnt vmcnt(8)
	s_waitcnt lgkmcnt(0)
	s_barrier
	s_nop 0
	s_waitcnt lgkmcnt(0)
	v_mfma_f32_16x16x32_bf16 v[62:65], v[146:149], v[182:185], v[62:65]
	v_mfma_f32_16x16x32_bf16 v[58:61], v[154:157], v[182:185], v[58:61]
	v_mfma_f32_16x16x32_bf16 v[54:57], v[146:149], v[194:197], v[54:57]
	v_mfma_f32_16x16x32_bf16 v[50:53], v[154:157], v[194:197], v[50:53]
	v_mfma_f32_16x16x32_bf16 v[38:41], v[146:149], v[202:205], v[38:41]
	v_mfma_f32_16x16x32_bf16 v[34:37], v[154:157], v[202:205], v[34:37]
	v_mfma_f32_16x16x32_bf16 v[22:25], v[146:149], v[216:219], v[22:25]
	v_mfma_f32_16x16x32_bf16 v[18:21], v[154:157], v[216:219], v[18:21]
	v_mfma_f32_16x16x32_bf16 v[62:65], v[150:153], v[190:193], v[62:65]
	v_mfma_f32_16x16x32_bf16 v[58:61], v[158:161], v[190:193], v[58:61]
	v_mfma_f32_16x16x32_bf16 v[54:57], v[150:153], v[198:201], v[54:57]
	v_mfma_f32_16x16x32_bf16 v[50:53], v[158:161], v[198:201], v[50:53]
	v_mfma_f32_16x16x32_bf16 v[38:41], v[150:153], v[212:215], v[38:41]
	v_mfma_f32_16x16x32_bf16 v[34:37], v[158:161], v[212:215], v[34:37]
	v_mfma_f32_16x16x32_bf16 v[22:25], v[150:153], v[220:223], v[22:25]
	v_mfma_f32_16x16x32_bf16 v[18:21], v[158:161], v[220:223], v[18:21]
	s_nop 0
	s_nop 0
	v_mfma_f32_16x16x32_bf16 v[46:49], v[162:165], v[182:185], v[46:49]
	v_mfma_f32_16x16x32_bf16 v[42:45], v[170:173], v[182:185], v[42:45]
	v_mfma_f32_16x16x32_bf16 v[30:33], v[162:165], v[194:197], v[30:33]
	v_mfma_f32_16x16x32_bf16 v[26:29], v[170:173], v[194:197], v[26:29]
	v_mfma_f32_16x16x32_bf16 v[14:17], v[162:165], v[202:205], v[14:17]
	v_mfma_f32_16x16x32_bf16 v[10:13], v[170:173], v[202:205], v[10:13]
	v_mfma_f32_16x16x32_bf16 v[6:9], v[162:165], v[216:219], v[6:9]
	v_mfma_f32_16x16x32_bf16 v[2:5], v[170:173], v[216:219], v[2:5]
	v_mfma_f32_16x16x32_bf16 v[46:49], v[166:169], v[190:193], v[46:49]
	v_mfma_f32_16x16x32_bf16 v[42:45], v[174:177], v[190:193], v[42:45]
	v_mfma_f32_16x16x32_bf16 v[30:33], v[166:169], v[198:201], v[30:33]
	v_mfma_f32_16x16x32_bf16 v[26:29], v[174:177], v[198:201], v[26:29]
	v_mfma_f32_16x16x32_bf16 v[14:17], v[166:169], v[212:215], v[14:17]
	v_mfma_f32_16x16x32_bf16 v[10:13], v[174:177], v[212:215], v[10:13]
	v_mfma_f32_16x16x32_bf16 v[6:9], v[166:169], v[220:223], v[6:9]
	v_mfma_f32_16x16x32_bf16 v[2:5], v[174:177], v[220:223], v[2:5]
	s_nop 0
	s_barrier
	s_add_i32 vcc_lo, vcc_lo, 2
	s_add_u32 s61, s61, 0x100
	s_addc_u32 s63, s63, 0
	s_add_u32 s68, s68, 0x100
	s_addc_u32 s69, s69, 0
	s_cmp_gt_u32 vcc_lo, 13
	s_cbranch_scc0 .LBB0_1086
	s_and_b64 vcc, exec, s[56:57]
	s_cbranch_vccz .LBB0_1089
	s_barrier

; #define PG8_STAGE(bufoff, gbase, voff) do { _Pragma("unroll") for (int _i = 0; _i < 2; ++_i) \
;         __builtin_amdgcn_global_load_lds((const unsigned*)((const char*)(gbase) + (voff)[_i]), (LAS unsigned*)(lds + (bufoff) + ldsw + _i * 8192), 16, 0, 0); } while (0)
; #define PG8_LDA(dst, b, h) do { _Pragma("unroll") for (int m = 0; m < 4; ++m) _Pragma("unroll") for (int k = 0; k < 2; ++k) dst[m][k] = *(const LAS bf16x8*)(lds + PG8_SA(b, h) + aoff + m * 2048 + k * 1024); } while (0)
; #define PG8_LDB(dst, b, h) do { _Pragma("unroll") for (int n = 0; n < 2; ++n) _Pragma("unroll") for (int k = 0; k < 2; ++k) dst[n][k] = *(const LAS bf16x8*)(lds + PG8_SB(b, h) + boff + n * 2048 + k * 1024); } while (0)
; #define PG8_MMA(ai, bj, At, Bt) do { __builtin_amdgcn_s_setprio(1); _Pragma("unroll") for (int m = 0; m < 4; ++m) _Pragma("unroll") for (int n = 0; n < 2; ++n) _Pragma("unroll") for (int k = 0; k < 2; ++k) \
;         acc[ai][bj][m][n] = __builtin_amdgcn_mfma_f32_16x16x32_bf16(Bt[n][k], At[m][k], acc[ai][bj][m][n], 0, 0, 0); __builtin_amdgcn_s_setprio(0); } while (0)
; #define PG8_WAIT_V(n) asm volatile("s_waitcnt vmcnt(" #n ")" ::: "memory")
; #define PG8_WAIT_L(n) asm volatile("s_waitcnt lgkmcnt(" #n ")" ::: "memory")
; #define PG8_BAR __builtin_amdgcn_s_barrier()
; #define PG8_SCHED __builtin_amdgcn_sched_barrier(0)
; template <class Epi, class Sched>
; DI void gemm_phase(LAS unsigned char* lds, const int K, const Sched& S, const Epi& E) {
;     ...
;             const bool last = (t == nt - 2);
;             const char* a1 = cA + (size_t)(t + 1) * kstep;
;             const char* a2 = last ? nA : cA + (size_t)(t + 2) * kstep; const char* b2 = last ? nB : cB + (size_t)(t + 2) * kstep;
;             const char* a3 = a2 + kstep; const char* b3 = b2 + kstep;
;             PG8_LDB(B0, 0, 0); PG8_LDB(B1, 0, 1); PG8_SCHED; PG8_LDA(At, 0, 0); PG8_STAGE(PG8_SA(1, 1), a1 + hstep, voffA);
;             PG8_WAIT_V(8); PG8_WAIT_L(0); PG8_BAR; PG8_MMA(0, 0, At, B0); PG8_MMA(0, 1, At, B1); PG8_BAR; PG8_SCHED;
;             PG8_LDA(At, 0, 1); PG8_STAGE(PG8_SB(0, 0), b2, voffB); PG8_STAGE(PG8_SB(0, 1), b2 + hstep, voffB); PG8_STAGE(PG8_SA(0, 0), a2, voffA);
;             PG8_WAIT_V(8); PG8_WAIT_L(0); PG8_BAR; PG8_MMA(1, 0, At, B0); PG8_MMA(1, 1, At, B1); PG8_BAR; PG8_SCHED;
.LBB0_1204:
	s_add_u32 s60, s58, 0x100
	s_addc_u32 s61, s59, 0
	s_add_i32 s48, 0, 0x10000
	s_cmp_eq_u32 s85, 40
	s_cselect_b32 s65, s55, s61
	s_cselect_b32 s64, s54, s60
	v_add_u32_e32 v145, s48, v143
	s_cselect_b32 s63, s57, s84
	s_cselect_b32 s62, s56, s83
	s_add_i32 s86, 0, 0x14000
	ds_read_b128 v[146:149], v145
	ds_read_b128 v[150:153], v145 offset:1024
	ds_read_b128 v[154:157], v145 offset:2048
	ds_read_b128 v[158:161], v145 offset:3072
	v_add_u32_e32 v145, s86, v143
	ds_read_b128 v[162:165], v145
	ds_read_b128 v[166:169], v145 offset:1024
	ds_read_b128 v[170:173], v145 offset:2048
	ds_read_b128 v[174:177], v145 offset:3072
	s_nop 0
	s_add_i32 m0, s71, 0xc000
	ds_read_b128 v[182:185], v144
	ds_read_b128 v[190:193], v144 offset:1024
	ds_read_b128 v[194:197], v144 offset:2048
	ds_read_b128 v[198:201], v144 offset:3072
	ds_read_b128 v[202:205], v144 offset:4096
	ds_read_b128 v[212:215], v144 offset:5120
	ds_read_b128 v[216:219], v144 offset:6144
	ds_read_b128 v[220:223], v144 offset:7168
	global_load_lds_dwordx4 v140, s[58:59]
	s_nop 0
	s_add_i32 m0, s71, 0xe000
	s_nop 0
	global_load_lds_dwordx4 v138, s[58:59]
	s_waitcnt vmcnt(8)
	s_waitcnt lgkmcnt(0)
	s_barrier
	s_nop 0
	s_waitcnt lgkmcnt(0)
	v_mfma_f32_16x16x32_bf16 v[126:129], v[146:149], v[182:185], v[126:129]
	v_mfma_f32_16x16x32_bf16 v[122:125], v[154:157], v[182:185], v[122:125]
	v_mfma_f32_16x16x32_bf16 v[118:121], v[146:149], v[194:197], v[118:121]
	v_mfma_f32_16x16x32_bf16 v[114:117], v[154:157], v[194:197], v[114:117]
	v_mfma_f32_16x16x32_bf16 v[102:105], v[146:149], v[202:205], v[102:105]
	v_mfma_f32_16x16x32_bf16 v[98:101], v[154:157], v[202:205], v[98:101]
	v_mfma_f32_16x16x32_bf16 v[86:89], v[146:149], v[216:219], v[86:89]
	v_mfma_f32_16x16x32_bf16 v[82:85], v[154:157], v[216:219], v[82:85]
	v_mfma_f32_16x16x32_bf16 v[126:129], v[150:153], v[190:193], v[126:129]
	v_mfma_f32_16x16x32_bf16 v[122:125], v[158:161], v[190:193], v[122:125]
	v_mfma_f32_16x16x32_bf16 v[118:121], v[150:153], v[198:201], v[118:121]
	v_mfma_f32_16x16x32_bf16 v[114:117], v[158:161], v[198:201], v[114:117]
	v_mfma_f32_16x16x32_bf16 v[102:105], v[150:153], v[212:215], v[102:105]
	v_mfma_f32_16x16x32_bf16 v[98:101], v[158:161], v[212:215], v[98:101]
	v_mfma_f32_16x16x32_bf16 v[86:89], v[150:153], v[220:223], v[86:89]
	v_mfma_f32_16x16x32_bf16 v[82:85], v[158:161], v[220:223], v[82:85]
	s_nop 0
	s_nop 0
	v_mfma_f32_16x16x32_bf16 v[110:113], v[162:165], v[182:185], v[110:113]
	v_mfma_f32_16x16x32_bf16 v[106:109], v[170:173], v[182:185], v[106:109]
	v_mfma_f32_16x16x32_bf16 v[94:97], v[162:165], v[194:197], v[94:97]
	v_mfma_f32_16x16x32_bf16 v[90:93], v[170:173], v[194:197], v[90:93]
	v_mfma_f32_16x16x32_bf16 v[78:81], v[162:165], v[202:205], v[78:81]
	v_mfma_f32_16x16x32_bf16 v[74:77], v[170:173], v[202:205], v[74:77]
	v_mfma_f32_16x16x32_bf16 v[70:73], v[162:165], v[216:219], v[70:73]
	v_mfma_f32_16x16x32_bf16 v[66:69], v[170:173], v[216:219], v[66:69]
	v_mfma_f32_16x16x32_bf16 v[110:113], v[166:169], v[190:193], v[110:113]
	v_mfma_f32_16x16x32_bf16 v[106:109], v[174:177], v[190:193], v[106:109]
	v_mfma_f32_16x16x32_bf16 v[94:97], v[166:169], v[198:201], v[94:97]
	v_mfma_f32_16x16x32_bf16 v[90:93], v[174:177], v[198:201], v[90:93]
	v_mfma_f32_16x16x32_bf16 v[78:81], v[166:169], v[212:215], v[78:81]
	v_mfma_f32_16x16x32_bf16 v[74:77], v[174:177], v[212:215], v[74:77]
	v_mfma_f32_16x16x32_bf16 v[70:73], v[166:169], v[220:223], v[70:73]
	v_mfma_f32_16x16x32_bf16 v[66:69], v[174:177], v[220:223], v[66:69]
	s_nop 0
	s_barrier
	s_add_i32 s48, s48, s69
	s_nop 0
	s_mov_b32 m0, s48
	ds_read_b128 v[182:185], v144 offset:16384
	ds_read_b128 v[190:193], v144 offset:17408
	ds_read_b128 v[194:197], v144 offset:18432
	ds_read_b128 v[198:201], v144 offset:19456
	ds_read_b128 v[202:205], v144 offset:20480
	ds_read_b128 v[212:215], v144 offset:21504
	ds_read_b128 v[216:219], v144 offset:22528
	ds_read_b128 v[220:223], v144 offset:23552
	global_load_lds_dwordx4 v134, s[62:63]
	s_add_i32 m0, s48, 0x2000
	s_add_u32 s48, s62, 0xb0000
	s_nop 0
	s_addc_u32 s49, s63, 0
	s_add_i32 s58, s86, s69
	global_load_lds_dwordx4 v130, s[62:63]
	s_nop 0
	s_mov_b32 m0, s58
	s_nop 0
	global_load_lds_dwordx4 v134, s[48:49]
	s_nop 0
	s_add_i32 m0, s58, 0x2000
	s_nop 0
	global_load_lds_dwordx4 v130, s[48:49]
	s_nop 0
	s_add_u32 s98, s64, s90
	s_addc_u32 s99, s65, s91
	s_mov_b32 m0, s71
	s_nop 0
	global_load_lds_dwordx4 v136, s[64:65]
	s_mov_b32 m0, s72
	s_nop 0
	global_load_lds_dwordx4 v132, s[64:65]
	s_waitcnt vmcnt(8)
	s_waitcnt lgkmcnt(0)
	s_barrier
; #define PG8_STAGE(bufoff, gbase, voff) do { _Pragma("unroll") for (int _i = 0; _i < 2; ++_i) \
;         __builtin_amdgcn_global_load_lds((const unsigned*)((const char*)(gbase) + (voff)[_i]), (LAS unsigned*)(lds + (bufoff) + ldsw + _i * 8192), 16, 0, 0); } while (0)
; #define PG8_LDA(dst, b, h) do { _Pragma("unroll") for (int m = 0; m < 4; ++m) _Pragma("unroll") for (int k = 0; k < 2; ++k) dst[m][k] = *(const LAS bf16x8*)(lds + PG8_SA(b, h) + aoff + m * 2048 + k * 1024); } while (0)
; #define PG8_LDB(dst, b, h) do { _Pragma("unroll") for (int n = 0; n < 2; ++n) _Pragma("unroll") for (int k = 0; k < 2; ++k) dst[n][k] = *(const LAS bf16x8*)(lds + PG8_SB(b, h) + boff + n * 2048 + k * 1024); } while (0)
; #define PG8_MMA(ai, bj, At, Bt) do { __builtin_amdgcn_s_setprio(1); _Pragma("unroll") for (int m = 0; m < 4; ++m) _Pragma("unroll") for (int n = 0; n < 2; ++n) _Pragma("unroll") for (int k = 0; k < 2; ++k) \
;         acc[ai][bj][m][n] = __builtin_amdgcn_mfma_f32_16x16x32_bf16(Bt[n][k], At[m][k], acc[ai][bj][m][n], 0, 0, 0); __builtin_amdgcn_s_setprio(0); } while (0)
; #define PG8_WAIT_V(n) asm volatile("s_waitcnt vmcnt(" #n ")" ::: "memory")
; #define PG8_WAIT_L(n) asm volatile("s_waitcnt lgkmcnt(" #n ")" ::: "memory")
; #define PG8_BAR __builtin_amdgcn_s_barrier()
; #define PG8_SCHED __builtin_amdgcn_sched_barrier(0)
; template <class Epi, class Sched>
; DI void gemm_phase(LAS unsigned char* lds, const int K, const Sched& S, const Epi& E) {
;     ...
;             PG8_WAIT_V(8); PG8_WAIT_L(0); PG8_BAR; PG8_MMA(1, 0, At, B0); PG8_MMA(1, 1, At, B1); PG8_BAR; PG8_SCHED;
;             PG8_LDB(B0, 1, 0); PG8_LDB(B1, 1, 1); PG8_SCHED; PG8_LDA(At, 1, 0); PG8_STAGE(PG8_SA(0, 1), a2 + hstep, voffA);
;             PG8_WAIT_V(8); PG8_WAIT_L(0); PG8_BAR; PG8_MMA(0, 0, At, B0); PG8_MMA(0, 1, At, B1); PG8_BAR; PG8_SCHED;
	s_nop 0
	s_waitcnt lgkmcnt(0)
	v_mfma_f32_16x16x32_bf16 v[62:65], v[146:149], v[182:185], v[62:65]
	v_mfma_f32_16x16x32_bf16 v[58:61], v[154:157], v[182:185], v[58:61]
	v_mfma_f32_16x16x32_bf16 v[54:57], v[146:149], v[194:197], v[54:57]
	v_mfma_f32_16x16x32_bf16 v[50:53], v[154:157], v[194:197], v[50:53]
	v_mfma_f32_16x16x32_bf16 v[38:41], v[146:149], v[202:205], v[38:41]
	v_mfma_f32_16x16x32_bf16 v[34:37], v[154:157], v[202:205], v[34:37]
	v_mfma_f32_16x16x32_bf16 v[22:25], v[146:149], v[216:219], v[22:25]
	v_mfma_f32_16x16x32_bf16 v[18:21], v[154:157], v[216:219], v[18:21]
	v_mfma_f32_16x16x32_bf16 v[62:65], v[150:153], v[190:193], v[62:65]
	v_mfma_f32_16x16x32_bf16 v[58:61], v[158:161], v[190:193], v[58:61]
	v_mfma_f32_16x16x32_bf16 v[54:57], v[150:153], v[198:201], v[54:57]
	v_mfma_f32_16x16x32_bf16 v[50:53], v[158:161], v[198:201], v[50:53]
	v_mfma_f32_16x16x32_bf16 v[38:41], v[150:153], v[212:215], v[38:41]
	v_mfma_f32_16x16x32_bf16 v[34:37], v[158:161], v[212:215], v[34:37]
	v_mfma_f32_16x16x32_bf16 v[22:25], v[150:153], v[220:223], v[22:25]
	v_mfma_f32_16x16x32_bf16 v[18:21], v[158:161], v[220:223], v[18:21]
	s_nop 0
	s_nop 0
	v_mfma_f32_16x16x32_bf16 v[46:49], v[162:165], v[182:185], v[46:49]
	v_mfma_f32_16x16x32_bf16 v[42:45], v[170:173], v[182:185], v[42:45]
	v_mfma_f32_16x16x32_bf16 v[30:33], v[162:165], v[194:197], v[30:33]
	v_mfma_f32_16x16x32_bf16 v[26:29], v[170:173], v[194:197], v[26:29]
	v_mfma_f32_16x16x32_bf16 v[14:17], v[162:165], v[202:205], v[14:17]
	v_mfma_f32_16x16x32_bf16 v[10:13], v[170:173], v[202:205], v[10:13]
	v_mfma_f32_16x16x32_bf16 v[6:9], v[162:165], v[216:219], v[6:9]
	v_mfma_f32_16x16x32_bf16 v[2:5], v[170:173], v[216:219], v[2:5]
	v_mfma_f32_16x16x32_bf16 v[46:49], v[166:169], v[190:193], v[46:49]
	v_mfma_f32_16x16x32_bf16 v[42:45], v[174:177], v[190:193], v[42:45]
	v_mfma_f32_16x16x32_bf16 v[30:33], v[166:169], v[198:201], v[30:33]
	v_mfma_f32_16x16x32_bf16 v[26:29], v[174:177], v[198:201], v[26:29]
	v_mfma_f32_16x16x32_bf16 v[14:17], v[166:169], v[212:215], v[14:17]
	v_mfma_f32_16x16x32_bf16 v[10:13], v[174:177], v[212:215], v[10:13]
	v_mfma_f32_16x16x32_bf16 v[6:9], v[166:169], v[220:223], v[6:9]
	v_mfma_f32_16x16x32_bf16 v[2:5], v[174:177], v[220:223], v[2:5]
	s_nop 0
	s_barrier
	s_add_i32 s58, 0, 0x18000
	v_add_u32_e32 v145, s58, v143
	s_add_i32 s59, 0, 0x1c000
	ds_read_b128 v[146:149], v145
	ds_read_b128 v[150:153], v145 offset:1024
	ds_read_b128 v[154:157], v145 offset:2048
	ds_read_b128 v[158:161], v145 offset:3072
	v_add_u32_e32 v145, s59, v143
	ds_read_b128 v[162:165], v145
	ds_read_b128 v[166:169], v145 offset:1024
	ds_read_b128 v[170:173], v145 offset:2048
	ds_read_b128 v[174:177], v145 offset:3072
	s_add_u32 s48, s64, 0xb0000
	s_addc_u32 s49, s65, 0
	s_mov_b32 m0, s73
	s_nop 0
	ds_read_b128 v[182:185], v144 offset:32768
	ds_read_b128 v[190:193], v144 offset:33792
	ds_read_b128 v[194:197], v144 offset:34816
	ds_read_b128 v[198:201], v144 offset:35840
	ds_read_b128 v[202:205], v144 offset:36864
	ds_read_b128 v[212:215], v144 offset:37888
	ds_read_b128 v[216:219], v144 offset:38912
	ds_read_b128 v[220:223], v144 offset:39936
	global_load_lds_dwordx4 v136, s[48:49]
	s_nop 0
	s_mov_b32 m0, s74
	s_nop 0
	global_load_lds_dwordx4 v132, s[48:49]
	s_waitcnt vmcnt(8)
	s_waitcnt lgkmcnt(0)
	s_barrier
	s_nop 0
	s_waitcnt lgkmcnt(0)
	v_mfma_f32_16x16x32_bf16 v[126:129], v[146:149], v[182:185], v[126:129]
	v_mfma_f32_16x16x32_bf16 v[122:125], v[154:157], v[182:185], v[122:125]
	v_mfma_f32_16x16x32_bf16 v[118:121], v[146:149], v[194:197], v[118:121]
	v_mfma_f32_16x16x32_bf16 v[114:117], v[154:157], v[194:197], v[114:117]
	v_mfma_f32_16x16x32_bf16 v[102:105], v[146:149], v[202:205], v[102:105]
	v_mfma_f32_16x16x32_bf16 v[98:101], v[154:157], v[202:205], v[98:101]
	v_mfma_f32_16x16x32_bf16 v[86:89], v[146:149], v[216:219], v[86:89]
	v_mfma_f32_16x16x32_bf16 v[82:85], v[154:157], v[216:219], v[82:85]
	v_mfma_f32_16x16x32_bf16 v[126:129], v[150:153], v[190:193], v[126:129]
	v_mfma_f32_16x16x32_bf16 v[122:125], v[158:161], v[190:193], v[122:125]
	v_mfma_f32_16x16x32_bf16 v[118:121], v[150:153], v[198:201], v[118:121]
	v_mfma_f32_16x16x32_bf16 v[114:117], v[158:161], v[198:201], v[114:117]
	v_mfma_f32_16x16x32_bf16 v[102:105], v[150:153], v[212:215], v[102:105]
	v_mfma_f32_16x16x32_bf16 v[98:101], v[158:161], v[212:215], v[98:101]
	v_mfma_f32_16x16x32_bf16 v[86:89], v[150:153], v[220:223], v[86:89]
	v_mfma_f32_16x16x32_bf16 v[82:85], v[158:161], v[220:223], v[82:85]
	s_nop 0
	s_nop 0
	v_mfma_f32_16x16x32_bf16 v[110:113], v[162:165], v[182:185], v[110:113]
	v_mfma_f32_16x16x32_bf16 v[106:109], v[170:173], v[182:185], v[106:109]
	v_mfma_f32_16x16x32_bf16 v[94:97], v[162:165], v[194:197], v[94:97]
	v_mfma_f32_16x16x32_bf16 v[90:93], v[170:173], v[194:197], v[90:93]
	v_mfma_f32_16x16x32_bf16 v[78:81], v[162:165], v[202:205], v[78:81]
	v_mfma_f32_16x16x32_bf16 v[74:77], v[170:173], v[202:205], v[74:77]
	v_mfma_f32_16x16x32_bf16 v[70:73], v[162:165], v[216:219], v[70:73]
	v_mfma_f32_16x16x32_bf16 v[66:69], v[170:173], v[216:219], v[66:69]
	v_mfma_f32_16x16x32_bf16 v[110:113], v[166:169], v[190:193], v[110:113]
	v_mfma_f32_16x16x32_bf16 v[106:109], v[174:177], v[190:193], v[106:109]
	v_mfma_f32_16x16x32_bf16 v[94:97], v[166:169], v[198:201], v[94:97]
	v_mfma_f32_16x16x32_bf16 v[90:93], v[174:177], v[198:201], v[90:93]
	v_mfma_f32_16x16x32_bf16 v[78:81], v[166:169], v[212:215], v[78:81]
	v_mfma_f32_16x16x32_bf16 v[74:77], v[174:177], v[212:215], v[74:77]
	v_mfma_f32_16x16x32_bf16 v[70:73], v[166:169], v[220:223], v[70:73]
	v_mfma_f32_16x16x32_bf16 v[66:69], v[174:177], v[220:223], v[66:69]
	s_nop 0
	s_barrier
; #define PG8_STAGE(bufoff, gbase, voff) do { _Pragma("unroll") for (int _i = 0; _i < 2; ++_i) \
;         __builtin_amdgcn_global_load_lds((const unsigned*)((const char*)(gbase) + (voff)[_i]), (LAS unsigned*)(lds + (bufoff) + ldsw + _i * 8192), 16, 0, 0); } while (0)
; #define PG8_LDA(dst, b, h) do { _Pragma("unroll") for (int m = 0; m < 4; ++m) _Pragma("unroll") for (int k = 0; k < 2; ++k) dst[m][k] = *(const LAS bf16x8*)(lds + PG8_SA(b, h) + aoff + m * 2048 + k * 1024); } while (0)
; #define PG8_MMA(ai, bj, At, Bt) do { __builtin_amdgcn_s_setprio(1); _Pragma("unroll") for (int m = 0; m < 4; ++m) _Pragma("unroll") for (int n = 0; n < 2; ++n) _Pragma("unroll") for (int k = 0; k < 2; ++k) \
;         acc[ai][bj][m][n] = __builtin_amdgcn_mfma_f32_16x16x32_bf16(Bt[n][k], At[m][k], acc[ai][bj][m][n], 0, 0, 0); __builtin_amdgcn_s_setprio(0); } while (0)
; #define PG8_WAIT_V(n) asm volatile("s_waitcnt vmcnt(" #n ")" ::: "memory")
; #define PG8_WAIT_L(n) asm volatile("s_waitcnt lgkmcnt(" #n ")" ::: "memory")
; #define PG8_BAR __builtin_amdgcn_s_barrier()
; #define PG8_SCHED __builtin_amdgcn_sched_barrier(0)
; template <class Epi, class Sched>
; DI void gemm_phase(LAS unsigned char* lds, const int K, const Sched& S, const Epi& E) {
;     ...
;             PG8_LDA(At, 1, 1); PG8_STAGE(PG8_SB(1, 0), b3, voffB); PG8_STAGE(PG8_SB(1, 1), b3 + hstep, voffB); PG8_STAGE(PG8_SA(1, 0), a3, voffA);
;             PG8_WAIT_V(8); PG8_WAIT_L(0); PG8_BAR; PG8_MMA(1, 0, At, B0); PG8_MMA(1, 1, At, B1); PG8_BAR; PG8_SCHED;
;         }
;         if (wr == 0) PG8_BAR;
	s_add_i32 s48, s58, s69
	s_add_u32 s62, s62, 0x80
	s_addc_u32 s63, s63, 0
	s_mov_b32 m0, s48
	ds_read_b128 v[182:185], v144 offset:49152
	ds_read_b128 v[190:193], v144 offset:50176
	ds_read_b128 v[194:197], v144 offset:51200
	ds_read_b128 v[198:201], v144 offset:52224
	ds_read_b128 v[202:205], v144 offset:53248
	ds_read_b128 v[212:215], v144 offset:54272
	ds_read_b128 v[216:219], v144 offset:55296
	ds_read_b128 v[220:223], v144 offset:56320
	global_load_lds_dwordx4 v134, s[62:63]
	s_add_i32 m0, s48, 0x2000
	s_add_u32 s48, s62, 0xb0000
	s_nop 0
	s_addc_u32 s49, s63, 0
	s_add_i32 s58, s59, s69
	global_load_lds_dwordx4 v130, s[62:63]
	s_nop 0
	s_mov_b32 m0, s58
	s_nop 0
	global_load_lds_dwordx4 v134, s[48:49]
	s_nop 0
	s_add_i32 m0, s58, 0x2000
	s_nop 0
	global_load_lds_dwordx4 v130, s[48:49]
	s_nop 0
	s_mov_b32 m0, s77
	s_nop 0
	global_load_lds_dwordx4 v136, s[98:99]
	s_nop 0
	s_mov_b32 m0, s78
	s_nop 0
	global_load_lds_dwordx4 v132, s[98:99]
	s_waitcnt vmcnt(8)
	s_waitcnt lgkmcnt(0)
	s_barrier
	s_nop 0
	s_waitcnt lgkmcnt(0)
	v_mfma_f32_16x16x32_bf16 v[62:65], v[146:149], v[182:185], v[62:65]
	v_mfma_f32_16x16x32_bf16 v[58:61], v[154:157], v[182:185], v[58:61]
	v_mfma_f32_16x16x32_bf16 v[54:57], v[146:149], v[194:197], v[54:57]
	v_mfma_f32_16x16x32_bf16 v[50:53], v[154:157], v[194:197], v[50:53]
	v_mfma_f32_16x16x32_bf16 v[38:41], v[146:149], v[202:205], v[38:41]
	v_mfma_f32_16x16x32_bf16 v[34:37], v[154:157], v[202:205], v[34:37]
	v_mfma_f32_16x16x32_bf16 v[22:25], v[146:149], v[216:219], v[22:25]
	v_mfma_f32_16x16x32_bf16 v[18:21], v[154:157], v[216:219], v[18:21]
	v_mfma_f32_16x16x32_bf16 v[62:65], v[150:153], v[190:193], v[62:65]
	v_mfma_f32_16x16x32_bf16 v[58:61], v[158:161], v[190:193], v[58:61]
	v_mfma_f32_16x16x32_bf16 v[54:57], v[150:153], v[198:201], v[54:57]
	v_mfma_f32_16x16x32_bf16 v[50:53], v[158:161], v[198:201], v[50:53]
	v_mfma_f32_16x16x32_bf16 v[38:41], v[150:153], v[212:215], v[38:41]
	v_mfma_f32_16x16x32_bf16 v[34:37], v[158:161], v[212:215], v[34:37]
	v_mfma_f32_16x16x32_bf16 v[22:25], v[150:153], v[220:223], v[22:25]
	v_mfma_f32_16x16x32_bf16 v[18:21], v[158:161], v[220:223], v[18:21]
	s_nop 0
	s_nop 0
	v_mfma_f32_16x16x32_bf16 v[46:49], v[162:165], v[182:185], v[46:49]
	v_mfma_f32_16x16x32_bf16 v[42:45], v[170:173], v[182:185], v[42:45]
	v_mfma_f32_16x16x32_bf16 v[30:33], v[162:165], v[194:197], v[30:33]
	v_mfma_f32_16x16x32_bf16 v[26:29], v[170:173], v[194:197], v[26:29]
	v_mfma_f32_16x16x32_bf16 v[14:17], v[162:165], v[202:205], v[14:17]
	v_mfma_f32_16x16x32_bf16 v[10:13], v[170:173], v[202:205], v[10:13]
	v_mfma_f32_16x16x32_bf16 v[6:9], v[162:165], v[216:219], v[6:9]
	v_mfma_f32_16x16x32_bf16 v[2:5], v[170:173], v[216:219], v[2:5]
	v_mfma_f32_16x16x32_bf16 v[46:49], v[166:169], v[190:193], v[46:49]
	v_mfma_f32_16x16x32_bf16 v[42:45], v[174:177], v[190:193], v[42:45]
	v_mfma_f32_16x16x32_bf16 v[30:33], v[166:169], v[198:201], v[30:33]
	v_mfma_f32_16x16x32_bf16 v[26:29], v[174:177], v[198:201], v[26:29]
	v_mfma_f32_16x16x32_bf16 v[14:17], v[166:169], v[212:215], v[14:17]
	v_mfma_f32_16x16x32_bf16 v[10:13], v[174:177], v[212:215], v[10:13]
	v_mfma_f32_16x16x32_bf16 v[6:9], v[166:169], v[220:223], v[6:9]
	v_mfma_f32_16x16x32_bf16 v[2:5], v[174:177], v[220:223], v[2:5]
	s_nop 0
	s_barrier
	s_add_i32 s85, s85, 2
	s_add_u32 s83, s83, 0x100
	s_addc_u32 s84, s84, 0
	s_cmp_gt_u32 s85, 41
	s_mov_b64 s[58:59], s[60:61]
	s_cbranch_scc0 .LBB0_1204
	s_and_b64 vcc, exec, s[52:53]
	s_cbranch_vccz .LBB0_1207
	s_barrier
